# fused state+scan: a single wave per workgroup does the L1 invalidate at the workgroup-local seam (8 invalidates per CU serialize)
# speedup vs baseline: 1.0073x; 1.0073x over previous
.LBB0_252:
	s_mov_b64 s[6:7], s[84:85]
	s_mov_b32 s3, s72
	v_mbcnt_lo_u32_b32 v0, -1, 0
	v_mbcnt_hi_u32_b32 v0, -1, v0
	s_getreg_b32 s2, hwreg(HW_REG_HW_ID, 0, 6)
	s_lshl_b32 s2, s2, 2
	s_and_b32 s2, s2, 0xfc
	s_add_i32 s2, s2, 0
	s_add_i32 s2, s2, 0x23400
	v_mov_b32_e32 v2, s2
	ds_read_b32 v2, v2
	s_waitcnt vmcnt(0) lgkmcnt(0)
	v_sub_u32_e32 v0, 0, v0
	s_waitcnt vmcnt(0) lgkmcnt(0)
	s_barrier
	v_readfirstlane_b32 s2, v2
	s_lshl_b32 s2, s2, 6
	s_nop 0
	v_cmp_eq_u32_e32 vcc, s2, v0
	s_mov_b64 s[4:5], exec
	s_cbranch_vccz .LBB0_320
	buffer_inv sc1
	s_waitcnt vmcnt(0)
	s_branch .LBB0_320
	v_mov_b32_e32 v0, s86
	s_load_dwordx2 s[6:7], s[6:7], 0x110
	s_getreg_b32 s2, hwreg(HW_REG_XCC_ID, 0, 4)
	ds_read_b32 v3, v0
	v_mov_b32_e32 v0, s87
	ds_read_b32 v2, v0
	s_and_b32 s2, s2, 15
	s_waitcnt lgkmcnt(0)
	v_cmp_ne_u32_e32 vcc, 0, v3
	s_cbranch_vccnz .LBB0_262
	s_add_u32 s8, s6, 0x4400
	s_addc_u32 s9, s7, 0
	s_add_u32 s10, s6, 0x4500
	s_addc_u32 s11, s7, 0
	s_add_u32 s12, s6, 0x4600
	s_addc_u32 s13, s7, 0
	s_add_u32 s14, s6, 0x4700
	s_addc_u32 s15, s7, 0
	s_add_u32 s16, s6, 0x4800
	s_addc_u32 s17, s7, 0
	s_add_u32 s18, s6, 0x4900
	s_addc_u32 s19, s7, 0
	s_add_u32 s20, s6, 0x4a00
	s_addc_u32 s21, s7, 0
	s_add_u32 s22, s6, 0x4b00
	s_addc_u32 s23, s7, 0
	s_add_u32 s24, s6, 0x4c00
	s_addc_u32 s25, s7, 0
	s_add_u32 s26, s6, 0x4d00
	s_addc_u32 s27, s7, 0
	s_add_u32 s28, s6, 0x4e00
	s_addc_u32 s29, s7, 0
	s_add_u32 s30, s6, 0x4f00
	s_addc_u32 s31, s7, 0
	s_add_u32 s34, s6, 0x5000
	s_addc_u32 s35, s7, 0
	s_add_u32 s36, s6, 0x5100
	s_addc_u32 s37, s7, 0
	s_add_u32 s38, s6, 0x5200
	s_addc_u32 s39, s7, 0
	s_add_u32 s40, s6, 0x5300
	s_addc_u32 s41, s7, 0
	s_mov_b32 s45, 0x400000
	s_branch .LBB0_257
